# Infinity-Cache-aware unit order: P10 walks row tiles in reverse of P9's write order (most recently written H first)
# speedup vs baseline: 1.0015x; 1.0015x over previous
.LBB0_1263:
	s_or_b64 exec, exec, s[0:1]
	v_mov_b32_e32 v10, v211
	s_waitcnt lgkmcnt(0)
	s_barrier
	s_andn2_b64 vcc, exec, s[8:9]
	v_readfirstlane_b32 s20, v10
	s_cbranch_vccnz .LBB0_1284
	v_readlane_b32 s7, v255, 16
	s_lshr_b32 s21, s7, 1
	v_readlane_b32 s0, v254, 27
	s_or_b32 s0, s21, s0
	v_readlane_b32 s1, v254, 26
	s_mul_i32 s0, s0, s1
	v_readlane_b32 s1, v254, 22
	s_add_i32 s0, s0, s1
	s_ashr_i32 s1, s0, 31
	s_lshr_b32 s1, s1, 27
	s_add_i32 s1, s0, s1
	s_ashr_i32 s6, s1, 5
	s_lshl_b32 s6, s6, 3
	s_sub_i32 s7, s7, s6
	s_min_i32 s7, s7, 8
	s_abs_i32 s8, s7
	v_cvt_f32_u32_e32 v0, s8
	s_sub_i32 s10, 0, s8
	s_andn2_b32 s1, s1, 31
	s_sub_i32 s0, s0, s1
	v_rcp_iflag_f32_e32 v0, v0
	s_abs_i32 s1, s0
	s_xor_b32 s9, s0, s7
	s_ashr_i32 s9, s9, 31
	v_mul_f32_e32 v0, 0x4f7ffffe, v0
	v_cvt_u32_f32_e32 v0, v0
	s_nop 0
	v_readfirstlane_b32 s11, v0
	s_mul_i32 s10, s10, s11
	s_mul_hi_u32 s10, s11, s10
	s_add_i32 s11, s11, s10
	s_mul_hi_u32 s10, s1, s11
	s_mul_i32 s11, s10, s8
	s_sub_i32 s1, s1, s11
	s_add_i32 s12, s10, 1
	s_sub_i32 s11, s1, s8
	s_cmp_ge_u32 s1, s8
	s_cselect_b32 s10, s12, s10
	s_cselect_b32 s1, s11, s1
	s_add_i32 s11, s10, 1
	s_cmp_ge_u32 s1, s8
	s_cselect_b32 s1, s11, s10
	s_xor_b32 s1, s1, s9
	s_sub_i32 s76, s1, s9
	s_mul_i32 s1, s76, s7
	s_sub_i32 s0, s0, s1
	v_readlane_b32 s1, v255, 16
	s_sub_i32 s6, s1, s6
	s_add_i32 s6, s6, -8
	s_sub_i32 s0, 7, s0
	s_and_b64 vcc, exec, s[4:5]
	s_add_i32 s12, s6, s0
	s_cbranch_vccnz .LBB0_1266
	s_ashr_i32 s1, s12, 3
	s_mul_i32 s1, s1, 9
	s_and_b32 s0, s0, 7
	s_add_i32 s0, s0, s1
	s_add_i32 s12, s0, 1

.LBB0_1270:
	v_readlane_b32 s36, v252, 18
	s_add_i32 s64, s64, 1
	v_readlane_b32 s42, v252, 24
	s_mul_i32 s0, s64, s55
	v_readlane_b32 s37, v252, 19
	v_readlane_b32 s38, v252, 20
	v_readlane_b32 s39, v252, 21
	v_readlane_b32 s40, v252, 22
	v_readlane_b32 s41, v252, 23
	v_readlane_b32 s43, v252, 25
	s_mul_hi_u32 s1, s64, s42
	s_add_i32 s1, s1, s0
	s_mul_i32 s0, s64, s42
	v_readlane_b32 s6, v254, 57
	v_readlane_b32 s36, v252, 0
	v_readlane_b32 s7, v254, 58
	s_add_u32 s6, s0, s6
	v_readlane_b32 s37, v252, 1
	s_addc_u32 s7, s1, s59
	v_readlane_b32 s38, v252, 2
	v_mov_b64_e32 v[2:3], s[36:37]
	v_cmp_ge_i64_e64 s[0:1], s[6:7], v[2:3]
	v_cmp_lt_i64_e64 s[8:9], s[6:7], v[2:3]
	s_and_b64 vcc, exec, s[0:1]
	v_readlane_b32 s39, v252, 3
	v_readlane_b32 s40, v252, 4
	v_readlane_b32 s41, v252, 5
	v_readlane_b32 s42, v252, 6
	v_readlane_b32 s43, v252, 7
	v_readlane_b32 s44, v252, 8
	v_readlane_b32 s45, v252, 9
	v_readlane_b32 s46, v252, 10
	v_readlane_b32 s47, v252, 11
	v_readlane_b32 s48, v252, 12
	v_readlane_b32 s49, v252, 13
	v_readlane_b32 s50, v252, 14
	v_readlane_b32 s51, v252, 15
	s_cbranch_vccnz .LBB0_1273
	s_ashr_i32 s7, s6, 31
	s_lshr_b32 s7, s7, 29
	s_add_i32 s7, s6, s7
	s_ashr_i32 s10, s7, 3
	s_and_b32 s7, s7, -8
	s_sub_i32 s6, s6, s7
	s_lshr_b32 s7, s6, 31
	s_or_b32 s7, s21, s7
	s_mul_i32 s6, s7, s6
	s_add_i32 s6, s6, s10
	s_ashr_i32 s7, s6, 31
	s_lshr_b32 s7, s7, 27
	s_add_i32 s7, s6, s7
	s_ashr_i32 s10, s7, 5
	s_lshl_b32 s10, s10, 3
	v_readlane_b32 s11, v255, 16
	s_sub_i32 s11, s11, s10
	s_min_i32 s11, s11, 8
	s_abs_i32 s13, s11
	v_cvt_f32_u32_e32 v2, s13
	s_sub_i32 s19, 0, s13
	s_andn2_b32 s7, s7, 31
	s_sub_i32 s6, s6, s7
	v_rcp_iflag_f32_e32 v2, v2
	s_abs_i32 s7, s6
	s_xor_b32 s18, s6, s11
	s_ashr_i32 s18, s18, 31
	v_mul_f32_e32 v2, 0x4f7ffffe, v2
	v_cvt_u32_f32_e32 v2, v2
	s_nop 0
	v_readfirstlane_b32 s65, v2
	s_mul_i32 s19, s19, s65
	s_mul_hi_u32 s19, s65, s19
	s_add_i32 s65, s65, s19
	s_mul_hi_u32 s19, s7, s65
	s_mul_i32 s65, s19, s13
	s_sub_i32 s7, s7, s65
	s_add_i32 s74, s19, 1
	s_sub_i32 s65, s7, s13
	s_cmp_ge_u32 s7, s13
	s_cselect_b32 s19, s74, s19
	s_cselect_b32 s7, s65, s7
	s_add_i32 s65, s19, 1
	s_cmp_ge_u32 s7, s13
	s_cselect_b32 s7, s65, s19
	s_xor_b32 s7, s7, s18
	s_sub_i32 s65, s7, s18
	s_mul_i32 s7, s65, s11
	s_sub_i32 s6, s6, s7
	v_readlane_b32 s7, v255, 16
	s_sub_i32 s10, s7, s10
	s_add_i32 s10, s10, -8
	s_sub_i32 s6, 7, s6
	s_and_b64 vcc, exec, s[4:5]
	s_add_i32 s74, s6, s10
	s_cbranch_vccnz .LBB0_1273
	s_ashr_i32 s7, s74, 3
	s_mul_i32 s7, s7, 9
	s_and_b32 s6, s6, 7
	s_add_i32 s6, s6, s7
	s_add_i32 s74, s6, 1
